# LayerNorm epilogue residual loads streamed 6-deep; compress-MLP second layer weight-row loads issued 16 at a time behind counted waits
# speedup vs baseline: 1.0495x; 1.0159x over previous
;     __device__ __forceinline__ void operator()(f32x4 (&acc)[2][2][4][2], const Unit& u, int wr, int wc, int fr, int fq) const {
;     ...
;         const int row0 = u.pm * BM + wr * 64 + fr, col0 = u.pn * BM + wc * 32 + 4 * fq;
; #pragma unroll
;         for (int ai = 0; ai < 2; ++ai)
; #pragma unroll
;             for (int m = 0; m < 4; ++m) { const size_t off = (size_t)(row0 + ai * HALF + m * 16) * DM + col0; float sm = 0.f;
; #pragma unroll
;                 for (int bj = 0; bj < 2; ++bj)
; #pragma unroll
;                     for (int n = 0; n < 2; ++n) { const f32x4 x = *(const f32x4*)(xres + off + bj * HALF + n * 16); const f32x4 z = x * 1.4142135623730951f + acc[ai][bj][m][n];
;                         acc[ai][bj][m][n] = z; sm += (z[0] + z[1]) + (z[2] + z[3]); }
.LBB0_27:
	v_and_b32_e32 v146, 64, v239
	v_xor_b32_e32 v145, 16, v239
	v_add_u32_e32 v146, 64, v146
	v_cmp_lt_i32_e32 vcc, v145, v146
	s_lshl_b32 s19, s58, 8
	v_add_u32_e32 v144, s19, v133
	v_cndmask_b32_e32 v145, v239, v145, vcc
	v_lshlrev_b32_e32 v151, 2, v145
	v_xor_b32_e32 v145, 32, v239
	v_cmp_lt_i32_e32 vcc, v145, v146
	v_mov_b32_e32 v150, v234
	s_nop 0
	v_cndmask_b32_e32 v145, v239, v145, vcc
	v_lshlrev_b32_e32 v176, 2, v145
	v_ashrrev_i32_e32 v145, 31, v144
	v_lshlrev_b64 v[146:147], 13, v[144:145]
	v_lshl_add_u64 v[146:147], v[134:135], 0, v[146:147]
	v_add_co_u32_e32 v232, vcc, 0x160000, v146
	s_nop 1
	v_addc_co_u32_e32 v233, vcc, 0, v147, vcc
	global_load_dwordx4 v[216:219], v[232:233], off
	global_load_dwordx4 v[220:223], v[232:233], off offset:64
	global_load_dwordx4 v[224:227], v[232:233], off offset:512
	global_load_dwordx4 v[228:231], v[232:233], off offset:576
	v_mov_b32_e32 v232, v146
	v_mov_b32_e32 v233, v147
	global_load_dwordx4 v[196:199], v[232:233], off
	global_load_dwordx4 v[200:203], v[232:233], off offset:64
	global_load_dwordx4 v[204:207], v[232:233], off offset:512
	global_load_dwordx4 v[208:211], v[232:233], off offset:576
	v_add_co_u32_e32 v232, vcc, 0x20000, v146
	s_nop 1
	v_addc_co_u32_e32 v233, vcc, 0, v147, vcc
	global_load_dwordx4 v[212:215], v[232:233], off
	global_load_dwordx4 v[248:251], v[232:233], off offset:64
	s_waitcnt vmcnt(5)
	v_pk_fma_f32 v[128:129], v[198:199], s[72:73], v[128:129] op_sel_hi:[1,0,1]
	v_pk_fma_f32 v[126:127], v[196:197], s[72:73], v[126:127] op_sel_hi:[1,0,1]
	global_load_dwordx4 v[196:199], v[232:233], off offset:512
	s_waitcnt vmcnt(5)
	v_pk_fma_f32 v[124:125], v[202:203], s[72:73], v[124:125] op_sel_hi:[1,0,1]
	v_pk_fma_f32 v[122:123], v[200:201], s[72:73], v[122:123] op_sel_hi:[1,0,1]
	global_load_dwordx4 v[200:203], v[232:233], off offset:576
	s_waitcnt vmcnt(5)
	v_pk_fma_f32 v[120:121], v[206:207], s[72:73], v[120:121] op_sel_hi:[1,0,1]
	v_pk_fma_f32 v[118:119], v[204:205], s[72:73], v[118:119] op_sel_hi:[1,0,1]
	v_add_co_u32_e32 v232, vcc, 0x40000, v146
	s_nop 1
	v_addc_co_u32_e32 v233, vcc, 0, v147, vcc
	global_load_dwordx4 v[204:207], v[232:233], off
	s_waitcnt vmcnt(5)
	v_pk_fma_f32 v[116:117], v[210:211], s[72:73], v[116:117] op_sel_hi:[1,0,1]
	v_pk_fma_f32 v[114:115], v[208:209], s[72:73], v[114:115] op_sel_hi:[1,0,1]
	global_load_dwordx4 v[208:211], v[232:233], off offset:64
	s_waitcnt vmcnt(5)
	v_pk_fma_f32 v[112:113], v[214:215], s[72:73], v[112:113] op_sel_hi:[1,0,1]
	v_pk_fma_f32 v[110:111], v[212:213], s[72:73], v[110:111] op_sel_hi:[1,0,1]
	global_load_dwordx4 v[212:215], v[232:233], off offset:512
	s_waitcnt vmcnt(5)
	v_pk_fma_f32 v[108:109], v[250:251], s[72:73], v[108:109] op_sel_hi:[1,0,1]
	v_pk_fma_f32 v[106:107], v[248:249], s[72:73], v[106:107] op_sel_hi:[1,0,1]
	global_load_dwordx4 v[248:251], v[232:233], off offset:576
	s_waitcnt vmcnt(5)
	v_pk_fma_f32 v[104:105], v[198:199], s[72:73], v[104:105] op_sel_hi:[1,0,1]
	v_pk_fma_f32 v[102:103], v[196:197], s[72:73], v[102:103] op_sel_hi:[1,0,1]
	v_add_co_u32_e32 v232, vcc, 0x60000, v146
	s_nop 1
	v_addc_co_u32_e32 v233, vcc, 0, v147, vcc
	global_load_dwordx4 v[196:199], v[232:233], off
	s_waitcnt vmcnt(5)
	v_pk_fma_f32 v[100:101], v[202:203], s[72:73], v[100:101] op_sel_hi:[1,0,1]
	v_pk_fma_f32 v[98:99], v[200:201], s[72:73], v[98:99] op_sel_hi:[1,0,1]
	global_load_dwordx4 v[200:203], v[232:233], off offset:64
	s_waitcnt vmcnt(5)
	v_pk_fma_f32 v[96:97], v[206:207], s[72:73], v[96:97] op_sel_hi:[1,0,1]
	v_pk_fma_f32 v[94:95], v[204:205], s[72:73], v[94:95] op_sel_hi:[1,0,1]
	global_load_dwordx4 v[204:207], v[232:233], off offset:512
	s_waitcnt vmcnt(5)
	v_pk_fma_f32 v[92:93], v[210:211], s[72:73], v[92:93] op_sel_hi:[1,0,1]
	v_pk_fma_f32 v[90:91], v[208:209], s[72:73], v[90:91] op_sel_hi:[1,0,1]
	global_load_dwordx4 v[208:211], v[232:233], off offset:576
	s_waitcnt vmcnt(5)
	v_pk_fma_f32 v[88:89], v[214:215], s[72:73], v[88:89] op_sel_hi:[1,0,1]
	v_pk_fma_f32 v[86:87], v[212:213], s[72:73], v[86:87] op_sel_hi:[1,0,1]
	v_add_co_u32_e32 v232, vcc, 0x100000, v146
	s_nop 1
	v_addc_co_u32_e32 v233, vcc, 0, v147, vcc
	global_load_dwordx4 v[212:215], v[232:233], off
	s_waitcnt vmcnt(5)
	v_pk_fma_f32 v[84:85], v[250:251], s[72:73], v[84:85] op_sel_hi:[1,0,1]
	v_pk_fma_f32 v[82:83], v[248:249], s[72:73], v[82:83] op_sel_hi:[1,0,1]
	global_load_dwordx4 v[248:251], v[232:233], off offset:64
	s_waitcnt vmcnt(5)
	v_pk_fma_f32 v[80:81], v[198:199], s[72:73], v[80:81] op_sel_hi:[1,0,1]
	v_pk_fma_f32 v[78:79], v[196:197], s[72:73], v[78:79] op_sel_hi:[1,0,1]
	global_load_dwordx4 v[196:199], v[232:233], off offset:512
	s_waitcnt vmcnt(5)
	v_pk_fma_f32 v[76:77], v[202:203], s[72:73], v[76:77] op_sel_hi:[1,0,1]
	v_pk_fma_f32 v[74:75], v[200:201], s[72:73], v[74:75] op_sel_hi:[1,0,1]
	global_load_dwordx4 v[200:203], v[232:233], off offset:576
	s_waitcnt vmcnt(5)
	v_pk_fma_f32 v[72:73], v[206:207], s[72:73], v[72:73] op_sel_hi:[1,0,1]
	v_pk_fma_f32 v[70:71], v[204:205], s[72:73], v[70:71] op_sel_hi:[1,0,1]
	v_add_co_u32_e32 v232, vcc, 0x120000, v146
	s_nop 1
	v_addc_co_u32_e32 v233, vcc, 0, v147, vcc
	global_load_dwordx4 v[204:207], v[232:233], off
	s_waitcnt vmcnt(5)
	v_pk_fma_f32 v[68:69], v[210:211], s[72:73], v[68:69] op_sel_hi:[1,0,1]
	v_pk_fma_f32 v[66:67], v[208:209], s[72:73], v[66:67] op_sel_hi:[1,0,1]
	global_load_dwordx4 v[208:211], v[232:233], off offset:64
	s_waitcnt vmcnt(5)
	v_pk_fma_f32 v[64:65], v[214:215], s[72:73], v[64:65] op_sel_hi:[1,0,1]
	v_pk_fma_f32 v[62:63], v[212:213], s[72:73], v[62:63] op_sel_hi:[1,0,1]
	global_load_dwordx4 v[212:215], v[232:233], off offset:512
	s_waitcnt vmcnt(5)
;     __device__ __forceinline__ void operator()(f32x4 (&acc)[2][2][4][2], const Unit& u, int wr, int wc, int fr, int fq) const {
;     ...
;             for (int m = 0; m < 4; ++m) { const size_t off = (size_t)(row0 + ai * HALF + m * 16) * DM + col0; float sm = 0.f;
; #pragma unroll
;                 for (int bj = 0; bj < 2; ++bj)
; #pragma unroll
;                     for (int n = 0; n < 2; ++n) { const f32x4 x = *(const f32x4*)(xres + off + bj * HALF + n * 16); const f32x4 z = x * 1.4142135623730951f + acc[ai][bj][m][n];
;                         acc[ai][bj][m][n] = z; sm += (z[0] + z[1]) + (z[2] + z[3]); }
;                 sm += __shfl_xor(sm, 16); sm += __shfl_xor(sm, 32);
;                 const float mw = sm * (1.0f / 64.0f); float q = 0.f;
; #pragma unroll
;                 for (int bj = 0; bj < 2; ++bj)
; #pragma unroll
;                     for (int n = 0; n < 2; ++n) { const f32x4 d = acc[ai][bj][m][n] - mw; q += (d[0] * d[0] + d[1] * d[1]) + (d[2] * d[2] + d[3] * d[3]); }
;                 q += __shfl_xor(q, 16); q += __shfl_xor(q, 32);
;                 if (fq == 0) Pt[(ai * HALF + wr * 64 + m * 16 + fr) * 4 + wc] = (f32x2v){mw, q}; }
	v_pk_fma_f32 v[60:61], v[250:251], s[72:73], v[60:61] op_sel_hi:[1,0,1]
	v_pk_fma_f32 v[58:59], v[248:249], s[72:73], v[58:59] op_sel_hi:[1,0,1]
	global_load_dwordx4 v[248:251], v[232:233], off offset:576
	s_waitcnt vmcnt(5)
	v_pk_fma_f32 v[56:57], v[198:199], s[72:73], v[56:57] op_sel_hi:[1,0,1]
	v_pk_fma_f32 v[54:55], v[196:197], s[72:73], v[54:55] op_sel_hi:[1,0,1]
	v_add_co_u32_e32 v232, vcc, 0x140000, v146
	s_nop 1
	v_addc_co_u32_e32 v233, vcc, 0, v147, vcc
	global_load_dwordx4 v[196:199], v[232:233], off
	s_waitcnt vmcnt(5)
	v_pk_fma_f32 v[52:53], v[202:203], s[72:73], v[52:53] op_sel_hi:[1,0,1]
	v_pk_fma_f32 v[50:51], v[200:201], s[72:73], v[50:51] op_sel_hi:[1,0,1]
	global_load_dwordx4 v[200:203], v[232:233], off offset:64
	s_waitcnt vmcnt(5)
	v_pk_fma_f32 v[48:49], v[206:207], s[72:73], v[48:49] op_sel_hi:[1,0,1]
	v_pk_fma_f32 v[46:47], v[204:205], s[72:73], v[46:47] op_sel_hi:[1,0,1]
	global_load_dwordx4 v[204:207], v[232:233], off offset:512
	s_waitcnt vmcnt(5)
	v_pk_fma_f32 v[44:45], v[210:211], s[72:73], v[44:45] op_sel_hi:[1,0,1]
	v_pk_fma_f32 v[42:43], v[208:209], s[72:73], v[42:43] op_sel_hi:[1,0,1]
	global_load_dwordx4 v[208:211], v[232:233], off offset:576
	s_waitcnt vmcnt(5)
	v_pk_fma_f32 v[40:41], v[214:215], s[72:73], v[40:41] op_sel_hi:[1,0,1]
	v_pk_fma_f32 v[38:39], v[212:213], s[72:73], v[38:39] op_sel_hi:[1,0,1]
	s_waitcnt vmcnt(4)
	v_pk_fma_f32 v[36:37], v[250:251], s[72:73], v[36:37] op_sel_hi:[1,0,1]
	v_pk_fma_f32 v[34:35], v[248:249], s[72:73], v[34:35] op_sel_hi:[1,0,1]
	s_waitcnt vmcnt(3)
	v_pk_fma_f32 v[32:33], v[198:199], s[72:73], v[32:33] op_sel_hi:[1,0,1]
	v_pk_fma_f32 v[30:31], v[196:197], s[72:73], v[30:31] op_sel_hi:[1,0,1]
	s_waitcnt vmcnt(2)
	v_pk_fma_f32 v[28:29], v[202:203], s[72:73], v[28:29] op_sel_hi:[1,0,1]
	v_pk_fma_f32 v[26:27], v[200:201], s[72:73], v[26:27] op_sel_hi:[1,0,1]
	s_waitcnt vmcnt(1)
	v_pk_fma_f32 v[24:25], v[206:207], s[72:73], v[24:25] op_sel_hi:[1,0,1]
	v_pk_fma_f32 v[22:23], v[204:205], s[72:73], v[22:23] op_sel_hi:[1,0,1]
	s_waitcnt vmcnt(0)
	v_pk_fma_f32 v[20:21], v[210:211], s[72:73], v[20:21] op_sel_hi:[1,0,1]
	v_pk_fma_f32 v[18:19], v[208:209], s[72:73], v[18:19] op_sel_hi:[1,0,1]
	v_mov_b32_e32 v179, v129
	v_pk_mov_b32 v[148:149], v[126:127], v[128:129] op_sel:[1,0]
	v_mov_b32_e32 v178, v126
	v_pk_add_f32 v[148:149], v[148:149], v[178:179]
	v_add_f32_e32 v148, v148, v149
	v_add_f32_e32 v148, 0, v148
	v_mov_b32_e32 v181, v125
	v_pk_mov_b32 v[178:179], v[122:123], v[124:125] op_sel:[1,0]
	v_mov_b32_e32 v180, v122
	v_pk_add_f32 v[178:179], v[178:179], v[180:181]
	s_nop 0
	v_pk_add_f32 v[182:183], v[178:179], v[178:179] op_sel:[0,1] op_sel_hi:[1,0]
	v_add_f32_e32 v184, v118, v119
	v_add_f32_e32 v186, v120, v121
	v_mov_b32_e32 v185, v116
	v_mov_b32_e32 v149, v114
	v_mov_b32_e32 v183, v115
	v_mov_b32_e32 v187, v117
	v_pk_add_f32 v[148:149], v[148:149], v[182:183]
	v_pk_add_f32 v[178:179], v[184:185], v[186:187]
	s_nop 0
	v_pk_add_f32 v[148:149], v[148:149], v[178:179]
	s_nop 0
	v_add_f32_e32 v148, v148, v149
	ds_bpermute_b32 v149, v151, v148
	s_waitcnt lgkmcnt(0)
	v_add_f32_e32 v148, v148, v149
	ds_bpermute_b32 v149, v176, v148
	s_waitcnt lgkmcnt(0)
	v_add_f32_e32 v148, v148, v149
	v_fmamk_f32 v177, v148, 0xbc800000, v129
	v_fmamk_f32 v179, v148, 0xbc800000, v127
	v_fmamk_f32 v149, v148, 0xbc800000, v128
	v_fmamk_f32 v178, v148, 0xbc800000, v126
	v_mul_f32_e32 v179, v179, v179
	v_mul_f32_e32 v177, v177, v177
	v_fmac_f32_e32 v179, v178, v178
	v_fmac_f32_e32 v177, v149, v149
	v_fmamk_f32 v178, v148, 0xbc800000, v125
	v_fmamk_f32 v180, v148, 0xbc800000, v123
	v_add_f32_e32 v149, v179, v177
	v_fmamk_f32 v177, v148, 0xbc800000, v124
	v_fmamk_f32 v179, v148, 0xbc800000, v122
	v_mul_f32_e32 v180, v180, v180
	v_mul_f32_e32 v178, v178, v178
	v_fmac_f32_e32 v180, v179, v179
	v_fmac_f32_e32 v178, v177, v177
	v_add_f32_e32 v177, v180, v178
	v_fmamk_f32 v178, v148, 0xbc800000, v121
	v_fmamk_f32 v180, v148, 0xbc800000, v119
	v_add_f32_e32 v149, v149, v177
	v_fmamk_f32 v177, v148, 0xbc800000, v120
	v_fmamk_f32 v179, v148, 0xbc800000, v118
	v_mul_f32_e32 v180, v180, v180
	v_mul_f32_e32 v178, v178, v178
	v_fmac_f32_e32 v180, v179, v179
	v_fmac_f32_e32 v178, v177, v177
	v_add_f32_e32 v177, v180, v178
	v_fmamk_f32 v178, v148, 0xbc800000, v117
	v_fmamk_f32 v180, v148, 0xbc800000, v115
	v_add_f32_e32 v149, v177, v149
	v_fmamk_f32 v177, v148, 0xbc800000, v116
	v_fmamk_f32 v179, v148, 0xbc800000, v114
	v_mul_f32_e32 v180, v180, v180
	v_mul_f32_e32 v178, v178, v178
	v_fmac_f32_e32 v180, v179, v179
	v_fmac_f32_e32 v178, v177, v177
	v_add_f32_e32 v177, v180, v178
	v_add_f32_e32 v149, v177, v149
	ds_bpermute_b32 v177, v151, v149
	s_waitcnt lgkmcnt(0)
	v_add_f32_e32 v149, v149, v177
	ds_bpermute_b32 v177, v176, v149
	s_and_saveexec_b64 s[0:1], s[8:9]
	v_readlane_b32 s46, v253, 10
	s_cbranch_execz .LBB0_29
	v_mul_f32_e32 v148, 0x3c800000, v148
	s_waitcnt lgkmcnt(0)
	v_add_f32_e32 v149, v149, v177
	ds_write_b64 v175, v[148:149]
;     __device__ __forceinline__ void operator()(f32x4 (&acc)[2][2][4][2], const Unit& u, int wr, int wc, int fr, int fq) const {
;     ...
;             for (int m = 0; m < 4; ++m) { const size_t off = (size_t)(row0 + ai * HALF + m * 16) * DM + col0; float sm = 0.f;
; #pragma unroll
;                 for (int bj = 0; bj < 2; ++bj)
; #pragma unroll
;                     for (int n = 0; n < 2; ++n) { const f32x4 x = *(const f32x4*)(xres + off + bj * HALF + n * 16); const f32x4 z = x * 1.4142135623730951f + acc[ai][bj][m][n];
;                         acc[ai][bj][m][n] = z; sm += (z[0] + z[1]) + (z[2] + z[3]); }
;                 sm += __shfl_xor(sm, 16); sm += __shfl_xor(sm, 32);
;                 const float mw = sm * (1.0f / 64.0f); float q = 0.f;
; #pragma unroll
;                 for (int bj = 0; bj < 2; ++bj)
; #pragma unroll
;                     for (int n = 0; n < 2; ++n) { const f32x4 d = acc[ai][bj][m][n] - mw; q += (d[0] * d[0] + d[1] * d[1]) + (d[2] * d[2] + d[3] * d[3]); }
;                 q += __shfl_xor(q, 16); q += __shfl_xor(q, 32);
;                 if (fq == 0) Pt[(ai * HALF + wr * 64 + m * 16 + fr) * 4 + wc] = (f32x2v){mw, q}; }
.LBB0_29:
	s_or_b64 exec, exec, s[0:1]
	v_or_b32_e32 v148, 16, v144
	v_ashrrev_i32_e32 v149, 31, v148
	v_lshlrev_b64 v[148:149], 13, v[148:149]
	v_lshl_add_u64 v[148:149], v[134:135], 0, v[148:149]
	v_mov_b32_e32 v181, v113
	v_pk_mov_b32 v[178:179], v[110:111], v[112:113] op_sel:[1,0]
	v_mov_b32_e32 v180, v110
	v_pk_add_f32 v[178:179], v[178:179], v[180:181]
	s_waitcnt lgkmcnt(0)
	v_add_f32_e32 v177, v178, v179
	v_add_f32_e32 v182, 0, v177
	v_mov_b32_e32 v181, v109
	v_pk_mov_b32 v[178:179], v[106:107], v[108:109] op_sel:[1,0]
	v_mov_b32_e32 v180, v106
	v_pk_add_f32 v[178:179], v[178:179], v[180:181]
	s_nop 0
	v_pk_add_f32 v[184:185], v[178:179], v[178:179] op_sel:[0,1] op_sel_hi:[1,0]
	v_add_f32_e32 v186, v102, v103
	v_add_f32_e32 v188, v104, v105
	v_mov_b32_e32 v187, v100
	v_mov_b32_e32 v183, v98
	v_mov_b32_e32 v185, v99
	v_mov_b32_e32 v189, v101
	v_pk_add_f32 v[148:149], v[182:183], v[184:185]
	v_pk_add_f32 v[178:179], v[186:187], v[188:189]
	s_nop 0
	v_pk_add_f32 v[148:149], v[148:149], v[178:179]
	s_nop 0
	v_add_f32_e32 v148, v148, v149
	ds_bpermute_b32 v149, v151, v148
	s_waitcnt lgkmcnt(0)
	v_add_f32_e32 v148, v148, v149
	ds_bpermute_b32 v149, v176, v148
	s_waitcnt lgkmcnt(0)
	v_add_f32_e32 v148, v148, v149
	v_fmamk_f32 v177, v148, 0xbc800000, v113
	v_fmamk_f32 v179, v148, 0xbc800000, v111
	v_fmamk_f32 v149, v148, 0xbc800000, v112
	v_fmamk_f32 v178, v148, 0xbc800000, v110
	v_mul_f32_e32 v179, v179, v179
	v_mul_f32_e32 v177, v177, v177
	v_fmac_f32_e32 v179, v178, v178
	v_fmac_f32_e32 v177, v149, v149
	v_fmamk_f32 v178, v148, 0xbc800000, v109
	v_fmamk_f32 v180, v148, 0xbc800000, v107
	v_add_f32_e32 v149, v179, v177
	v_fmamk_f32 v177, v148, 0xbc800000, v108
	v_fmamk_f32 v179, v148, 0xbc800000, v106
	v_mul_f32_e32 v180, v180, v180
	v_mul_f32_e32 v178, v178, v178
	v_fmac_f32_e32 v180, v179, v179
	v_fmac_f32_e32 v178, v177, v177
	v_add_f32_e32 v177, v180, v178
	v_fmamk_f32 v178, v148, 0xbc800000, v105
	v_fmamk_f32 v180, v148, 0xbc800000, v103
	v_add_f32_e32 v149, v149, v177
	v_fmamk_f32 v177, v148, 0xbc800000, v104
	v_fmamk_f32 v179, v148, 0xbc800000, v102
	v_mul_f32_e32 v180, v180, v180
	v_mul_f32_e32 v178, v178, v178
	v_fmac_f32_e32 v180, v179, v179
	v_fmac_f32_e32 v178, v177, v177
	v_add_f32_e32 v177, v180, v178
	v_fmamk_f32 v178, v148, 0xbc800000, v101
	v_fmamk_f32 v180, v148, 0xbc800000, v99
	v_add_f32_e32 v149, v177, v149
	v_fmamk_f32 v177, v148, 0xbc800000, v100
	v_fmamk_f32 v179, v148, 0xbc800000, v98
	v_mul_f32_e32 v180, v180, v180
	v_mul_f32_e32 v178, v178, v178
	v_fmac_f32_e32 v180, v179, v179
	v_fmac_f32_e32 v178, v177, v177
	v_add_f32_e32 v177, v180, v178
	v_add_f32_e32 v149, v177, v149
	ds_bpermute_b32 v177, v151, v149
	s_waitcnt lgkmcnt(0)
	v_add_f32_e32 v149, v149, v177
	ds_bpermute_b32 v177, v176, v149
	s_and_saveexec_b64 s[0:1], s[8:9]
	s_cbranch_execz .LBB0_31
	v_mul_f32_e32 v148, 0x3c800000, v148
	s_waitcnt lgkmcnt(0)
	v_add_f32_e32 v149, v149, v177
	ds_write_b64 v175, v[148:149] offset:512
.LBB0_31:
	s_or_b64 exec, exec, s[0:1]
	v_or_b32_e32 v148, 32, v144
	v_ashrrev_i32_e32 v149, 31, v148
	v_lshlrev_b64 v[148:149], 13, v[148:149]
	v_lshl_add_u64 v[148:149], v[134:135], 0, v[148:149]
	v_mov_b32_e32 v181, v97
	v_pk_mov_b32 v[178:179], v[94:95], v[96:97] op_sel:[1,0]
	v_mov_b32_e32 v180, v94
	v_pk_add_f32 v[178:179], v[178:179], v[180:181]
	s_waitcnt lgkmcnt(0)
	v_add_f32_e32 v177, v178, v179
	v_add_f32_e32 v182, 0, v177
	v_mov_b32_e32 v181, v93
	v_pk_mov_b32 v[178:179], v[90:91], v[92:93] op_sel:[1,0]
	v_mov_b32_e32 v180, v90
	v_pk_add_f32 v[178:179], v[178:179], v[180:181]
	s_nop 0
	v_pk_add_f32 v[184:185], v[178:179], v[178:179] op_sel:[0,1] op_sel_hi:[1,0]
	v_add_f32_e32 v186, v86, v87
	v_add_f32_e32 v188, v88, v89
	v_mov_b32_e32 v187, v84
	v_mov_b32_e32 v183, v82
	v_mov_b32_e32 v185, v83
	v_mov_b32_e32 v189, v85
	v_pk_add_f32 v[148:149], v[182:183], v[184:185]
	v_pk_add_f32 v[178:179], v[186:187], v[188:189]
	s_nop 0
	v_pk_add_f32 v[148:149], v[148:149], v[178:179]
	s_nop 0
	v_add_f32_e32 v148, v148, v149
	ds_bpermute_b32 v149, v151, v148
	s_waitcnt lgkmcnt(0)
	v_add_f32_e32 v148, v148, v149
	ds_bpermute_b32 v149, v176, v148
	s_waitcnt lgkmcnt(0)
	v_add_f32_e32 v148, v148, v149
	v_fmamk_f32 v177, v148, 0xbc800000, v97
	v_fmamk_f32 v179, v148, 0xbc800000, v95
	v_fmamk_f32 v149, v148, 0xbc800000, v96
	v_fmamk_f32 v178, v148, 0xbc800000, v94
	v_mul_f32_e32 v179, v179, v179
	v_mul_f32_e32 v177, v177, v177
	v_fmac_f32_e32 v179, v178, v178
	v_fmac_f32_e32 v177, v149, v149
	v_fmamk_f32 v178, v148, 0xbc800000, v93
	v_fmamk_f32 v180, v148, 0xbc800000, v91
	v_add_f32_e32 v149, v179, v177
	v_fmamk_f32 v177, v148, 0xbc800000, v92
	v_fmamk_f32 v179, v148, 0xbc800000, v90
	v_mul_f32_e32 v180, v180, v180
	v_mul_f32_e32 v178, v178, v178
	v_fmac_f32_e32 v180, v179, v179
	v_fmac_f32_e32 v178, v177, v177
	v_add_f32_e32 v177, v180, v178
	v_fmamk_f32 v178, v148, 0xbc800000, v89
	v_fmamk_f32 v180, v148, 0xbc800000, v87
	v_add_f32_e32 v149, v149, v177
	v_fmamk_f32 v177, v148, 0xbc800000, v88
	v_fmamk_f32 v179, v148, 0xbc800000, v86
	v_mul_f32_e32 v180, v180, v180
	v_mul_f32_e32 v178, v178, v178
	v_fmac_f32_e32 v180, v179, v179
	v_fmac_f32_e32 v178, v177, v177
	v_add_f32_e32 v177, v180, v178
	v_fmamk_f32 v178, v148, 0xbc800000, v85
	v_fmamk_f32 v180, v148, 0xbc800000, v83
	v_add_f32_e32 v149, v177, v149
	v_fmamk_f32 v177, v148, 0xbc800000, v84
	v_fmamk_f32 v179, v148, 0xbc800000, v82
	v_mul_f32_e32 v180, v180, v180
	v_mul_f32_e32 v178, v178, v178
	v_fmac_f32_e32 v180, v179, v179
	v_fmac_f32_e32 v178, v177, v177
	v_add_f32_e32 v177, v180, v178
	v_add_f32_e32 v149, v177, v149
	ds_bpermute_b32 v177, v151, v149
	s_waitcnt lgkmcnt(0)
	v_add_f32_e32 v149, v149, v177
	ds_bpermute_b32 v177, v176, v149
	s_and_saveexec_b64 s[0:1], s[8:9]
	s_cbranch_execz .LBB0_33
	v_mul_f32_e32 v148, 0x3c800000, v148
	s_waitcnt lgkmcnt(0)
	v_add_f32_e32 v149, v149, v177
	ds_write_b64 v175, v[148:149] offset:1024
;     __device__ __forceinline__ void operator()(f32x4 (&acc)[2][2][4][2], const Unit& u, int wr, int wc, int fr, int fq) const {
;     ...
;             for (int m = 0; m < 4; ++m) { const size_t off = (size_t)(row0 + ai * HALF + m * 16) * DM + col0; float sm = 0.f;
; #pragma unroll
;                 for (int bj = 0; bj < 2; ++bj)
; #pragma unroll
;                     for (int n = 0; n < 2; ++n) { const f32x4 x = *(const f32x4*)(xres + off + bj * HALF + n * 16); const f32x4 z = x * 1.4142135623730951f + acc[ai][bj][m][n];
;                         acc[ai][bj][m][n] = z; sm += (z[0] + z[1]) + (z[2] + z[3]); }
;                 sm += __shfl_xor(sm, 16); sm += __shfl_xor(sm, 32);
;                 const float mw = sm * (1.0f / 64.0f); float q = 0.f;
; #pragma unroll
;                 for (int bj = 0; bj < 2; ++bj)
; #pragma unroll
;                     for (int n = 0; n < 2; ++n) { const f32x4 d = acc[ai][bj][m][n] - mw; q += (d[0] * d[0] + d[1] * d[1]) + (d[2] * d[2] + d[3] * d[3]); }
;                 q += __shfl_xor(q, 16); q += __shfl_xor(q, 32);
;                 if (fq == 0) Pt[(ai * HALF + wr * 64 + m * 16 + fr) * 4 + wc] = (f32x2v){mw, q}; }
.LBB0_33:
	s_or_b64 exec, exec, s[0:1]
	v_or_b32_e32 v148, 48, v144
	v_ashrrev_i32_e32 v149, 31, v148
	v_lshlrev_b64 v[148:149], 13, v[148:149]
	v_lshl_add_u64 v[148:149], v[134:135], 0, v[148:149]
	v_mov_b32_e32 v181, v81
	v_pk_mov_b32 v[178:179], v[78:79], v[80:81] op_sel:[1,0]
	v_mov_b32_e32 v180, v78
	v_pk_add_f32 v[178:179], v[178:179], v[180:181]
	s_waitcnt lgkmcnt(0)
	v_add_f32_e32 v177, v178, v179
	v_add_f32_e32 v182, 0, v177
	v_mov_b32_e32 v181, v77
	v_pk_mov_b32 v[178:179], v[74:75], v[76:77] op_sel:[1,0]
	v_mov_b32_e32 v180, v74
	v_pk_add_f32 v[178:179], v[178:179], v[180:181]
	s_nop 0
	v_pk_add_f32 v[184:185], v[178:179], v[178:179] op_sel:[0,1] op_sel_hi:[1,0]
	v_add_f32_e32 v186, v70, v71
	v_add_f32_e32 v188, v72, v73
	v_mov_b32_e32 v187, v68
	v_mov_b32_e32 v183, v66
	v_mov_b32_e32 v185, v67
	v_mov_b32_e32 v189, v69
	v_pk_add_f32 v[148:149], v[182:183], v[184:185]
	v_pk_add_f32 v[178:179], v[186:187], v[188:189]
	s_nop 0
	v_pk_add_f32 v[148:149], v[148:149], v[178:179]
	s_nop 0
	v_add_f32_e32 v148, v148, v149
	ds_bpermute_b32 v149, v151, v148
	s_waitcnt lgkmcnt(0)
	v_add_f32_e32 v148, v148, v149
	ds_bpermute_b32 v149, v176, v148
	s_waitcnt lgkmcnt(0)
	v_add_f32_e32 v148, v148, v149
	v_fmamk_f32 v177, v148, 0xbc800000, v81
	v_fmamk_f32 v179, v148, 0xbc800000, v79
	v_fmamk_f32 v149, v148, 0xbc800000, v80
	v_fmamk_f32 v178, v148, 0xbc800000, v78
	v_mul_f32_e32 v179, v179, v179
	v_mul_f32_e32 v177, v177, v177
	v_fmac_f32_e32 v179, v178, v178
	v_fmac_f32_e32 v177, v149, v149
	v_fmamk_f32 v178, v148, 0xbc800000, v77
	v_fmamk_f32 v180, v148, 0xbc800000, v75
	v_add_f32_e32 v149, v179, v177
	v_fmamk_f32 v177, v148, 0xbc800000, v76
	v_fmamk_f32 v179, v148, 0xbc800000, v74
	v_mul_f32_e32 v180, v180, v180
	v_mul_f32_e32 v178, v178, v178
	v_fmac_f32_e32 v180, v179, v179
	v_fmac_f32_e32 v178, v177, v177
	v_add_f32_e32 v177, v180, v178
	v_fmamk_f32 v178, v148, 0xbc800000, v73
	v_fmamk_f32 v180, v148, 0xbc800000, v71
	v_add_f32_e32 v149, v149, v177
	v_fmamk_f32 v177, v148, 0xbc800000, v72
	v_fmamk_f32 v179, v148, 0xbc800000, v70
	v_mul_f32_e32 v180, v180, v180
	v_mul_f32_e32 v178, v178, v178
	v_fmac_f32_e32 v180, v179, v179
	v_fmac_f32_e32 v178, v177, v177
	v_add_f32_e32 v177, v180, v178
	v_fmamk_f32 v178, v148, 0xbc800000, v69
	v_fmamk_f32 v180, v148, 0xbc800000, v67
	v_add_f32_e32 v149, v177, v149
	v_fmamk_f32 v177, v148, 0xbc800000, v68
	v_fmamk_f32 v179, v148, 0xbc800000, v66
	v_mul_f32_e32 v180, v180, v180
	v_mul_f32_e32 v178, v178, v178
	v_fmac_f32_e32 v180, v179, v179
	v_fmac_f32_e32 v178, v177, v177
	v_add_f32_e32 v177, v180, v178
	v_add_f32_e32 v149, v177, v149
	ds_bpermute_b32 v177, v151, v149
	s_waitcnt lgkmcnt(0)
	v_add_f32_e32 v149, v149, v177
	ds_bpermute_b32 v177, v176, v149
	s_and_saveexec_b64 s[0:1], s[8:9]
	s_cbranch_execz .LBB0_35
	v_mul_f32_e32 v148, 0x3c800000, v148
	s_waitcnt lgkmcnt(0)
	v_add_f32_e32 v149, v149, v177
	ds_write_b64 v175, v[148:149] offset:1536
.LBB0_35:
	s_or_b64 exec, exec, s[0:1]
	v_add_co_u32_e32 v178, vcc, 0x100000, v146
	s_mov_b64 s[0:1], 0x100000
	s_nop 0
	v_addc_co_u32_e32 v179, vcc, 0, v147, vcc
	v_lshl_add_u64 v[148:149], v[146:147], 0, s[0:1]
	v_mov_b32_e32 v181, v65
	v_pk_mov_b32 v[178:179], v[62:63], v[64:65] op_sel:[1,0]
	v_mov_b32_e32 v180, v62
	v_pk_add_f32 v[178:179], v[178:179], v[180:181]
	s_waitcnt lgkmcnt(0)
	v_add_f32_e32 v177, v178, v179
	v_add_f32_e32 v182, 0, v177
	v_mov_b32_e32 v181, v61
	v_pk_mov_b32 v[178:179], v[58:59], v[60:61] op_sel:[1,0]
	v_mov_b32_e32 v180, v58
	v_pk_add_f32 v[178:179], v[178:179], v[180:181]
	s_nop 0
	v_pk_add_f32 v[184:185], v[178:179], v[178:179] op_sel:[0,1] op_sel_hi:[1,0]
	v_add_f32_e32 v186, v54, v55
	v_add_f32_e32 v188, v56, v57
	v_mov_b32_e32 v187, v52
	v_mov_b32_e32 v183, v50
	v_mov_b32_e32 v185, v51
	v_mov_b32_e32 v189, v53
	v_pk_add_f32 v[148:149], v[182:183], v[184:185]
	v_pk_add_f32 v[178:179], v[186:187], v[188:189]
	s_nop 0
	v_pk_add_f32 v[148:149], v[148:149], v[178:179]
	s_nop 0
	v_add_f32_e32 v148, v148, v149
	ds_bpermute_b32 v149, v151, v148
	s_waitcnt lgkmcnt(0)
	v_add_f32_e32 v148, v148, v149
	ds_bpermute_b32 v149, v176, v148
	s_waitcnt lgkmcnt(0)
	v_add_f32_e32 v148, v148, v149
	v_fmamk_f32 v177, v148, 0xbc800000, v65
	v_fmamk_f32 v179, v148, 0xbc800000, v63
	v_fmamk_f32 v149, v148, 0xbc800000, v64
	v_fmamk_f32 v178, v148, 0xbc800000, v62
	v_mul_f32_e32 v179, v179, v179
	v_mul_f32_e32 v177, v177, v177
	v_fmac_f32_e32 v179, v178, v178
	v_fmac_f32_e32 v177, v149, v149
	v_fmamk_f32 v178, v148, 0xbc800000, v61
	v_fmamk_f32 v180, v148, 0xbc800000, v59
	v_add_f32_e32 v149, v179, v177
	v_fmamk_f32 v177, v148, 0xbc800000, v60
	v_fmamk_f32 v179, v148, 0xbc800000, v58
	v_mul_f32_e32 v180, v180, v180
	v_mul_f32_e32 v178, v178, v178
	v_fmac_f32_e32 v180, v179, v179
	v_fmac_f32_e32 v178, v177, v177
	v_add_f32_e32 v177, v180, v178
	v_fmamk_f32 v178, v148, 0xbc800000, v57
	v_fmamk_f32 v180, v148, 0xbc800000, v55
	v_add_f32_e32 v149, v149, v177
	v_fmamk_f32 v177, v148, 0xbc800000, v56
	v_fmamk_f32 v179, v148, 0xbc800000, v54
	v_mul_f32_e32 v180, v180, v180
	v_mul_f32_e32 v178, v178, v178
	v_fmac_f32_e32 v180, v179, v179
	v_fmac_f32_e32 v178, v177, v177
	v_add_f32_e32 v177, v180, v178
	v_fmamk_f32 v178, v148, 0xbc800000, v53
	v_fmamk_f32 v180, v148, 0xbc800000, v51
	v_add_f32_e32 v149, v177, v149
	v_fmamk_f32 v177, v148, 0xbc800000, v52
	v_fmamk_f32 v179, v148, 0xbc800000, v50
	v_mul_f32_e32 v180, v180, v180
	v_mul_f32_e32 v178, v178, v178
	v_fmac_f32_e32 v180, v179, v179
	v_fmac_f32_e32 v178, v177, v177
	v_add_f32_e32 v177, v180, v178
	v_add_f32_e32 v149, v177, v149
	ds_bpermute_b32 v177, v151, v149
	s_waitcnt lgkmcnt(0)
	v_add_f32_e32 v149, v149, v177
	ds_bpermute_b32 v177, v176, v149
	s_and_saveexec_b64 s[0:1], s[8:9]
	s_cbranch_execz .LBB0_37
	v_mul_f32_e32 v148, 0x3c800000, v148
	s_waitcnt lgkmcnt(0)
	v_add_f32_e32 v149, v149, v177
	ds_write_b64 v174, v[148:149]
;     __device__ __forceinline__ void operator()(f32x4 (&acc)[2][2][4][2], const Unit& u, int wr, int wc, int fr, int fq) const {
;     ...
;             for (int m = 0; m < 4; ++m) { const size_t off = (size_t)(row0 + ai * HALF + m * 16) * DM + col0; float sm = 0.f;
; #pragma unroll
;                 for (int bj = 0; bj < 2; ++bj)
; #pragma unroll
;                     for (int n = 0; n < 2; ++n) { const f32x4 x = *(const f32x4*)(xres + off + bj * HALF + n * 16); const f32x4 z = x * 1.4142135623730951f + acc[ai][bj][m][n];
;                         acc[ai][bj][m][n] = z; sm += (z[0] + z[1]) + (z[2] + z[3]); }
;                 sm += __shfl_xor(sm, 16); sm += __shfl_xor(sm, 32);
;                 const float mw = sm * (1.0f / 64.0f); float q = 0.f;
; #pragma unroll
;                 for (int bj = 0; bj < 2; ++bj)
; #pragma unroll
;                     for (int n = 0; n < 2; ++n) { const f32x4 d = acc[ai][bj][m][n] - mw; q += (d[0] * d[0] + d[1] * d[1]) + (d[2] * d[2] + d[3] * d[3]); }
;                 q += __shfl_xor(q, 16); q += __shfl_xor(q, 32);
;                 if (fq == 0) Pt[(ai * HALF + wr * 64 + m * 16 + fr) * 4 + wc] = (f32x2v){mw, q}; }
.LBB0_37:
	s_or_b64 exec, exec, s[0:1]
	v_add_co_u32_e32 v178, vcc, 0x120000, v146
	s_mov_b64 s[0:1], 0x120000
	s_nop 0
	v_addc_co_u32_e32 v179, vcc, 0, v147, vcc
	v_lshl_add_u64 v[148:149], v[146:147], 0, s[0:1]
	v_mov_b32_e32 v181, v49
	v_pk_mov_b32 v[178:179], v[46:47], v[48:49] op_sel:[1,0]
	v_mov_b32_e32 v180, v46
	v_pk_add_f32 v[178:179], v[178:179], v[180:181]
	s_waitcnt lgkmcnt(0)
	v_add_f32_e32 v177, v178, v179
	v_add_f32_e32 v182, 0, v177
	v_mov_b32_e32 v181, v45
	v_pk_mov_b32 v[178:179], v[42:43], v[44:45] op_sel:[1,0]
	v_mov_b32_e32 v180, v42
	v_pk_add_f32 v[178:179], v[178:179], v[180:181]
	s_nop 0
	v_pk_add_f32 v[184:185], v[178:179], v[178:179] op_sel:[0,1] op_sel_hi:[1,0]
	v_add_f32_e32 v186, v38, v39
	v_add_f32_e32 v188, v40, v41
	v_mov_b32_e32 v187, v36
	v_mov_b32_e32 v183, v34
	v_mov_b32_e32 v185, v35
	v_mov_b32_e32 v189, v37
	v_pk_add_f32 v[148:149], v[182:183], v[184:185]
	v_pk_add_f32 v[178:179], v[186:187], v[188:189]
	s_nop 0
	v_pk_add_f32 v[148:149], v[148:149], v[178:179]
	s_nop 0
	v_add_f32_e32 v148, v148, v149
	ds_bpermute_b32 v149, v151, v148
	s_waitcnt lgkmcnt(0)
	v_add_f32_e32 v148, v148, v149
	ds_bpermute_b32 v149, v176, v148
	s_waitcnt lgkmcnt(0)
	v_add_f32_e32 v148, v148, v149
	v_fmamk_f32 v177, v148, 0xbc800000, v49
	v_fmamk_f32 v179, v148, 0xbc800000, v47
	v_fmamk_f32 v149, v148, 0xbc800000, v48
	v_fmamk_f32 v178, v148, 0xbc800000, v46
	v_mul_f32_e32 v179, v179, v179
	v_mul_f32_e32 v177, v177, v177
	v_fmac_f32_e32 v179, v178, v178
	v_fmac_f32_e32 v177, v149, v149
	v_fmamk_f32 v178, v148, 0xbc800000, v45
	v_fmamk_f32 v180, v148, 0xbc800000, v43
	v_add_f32_e32 v149, v179, v177
	v_fmamk_f32 v177, v148, 0xbc800000, v44
	v_fmamk_f32 v179, v148, 0xbc800000, v42
	v_mul_f32_e32 v180, v180, v180
	v_mul_f32_e32 v178, v178, v178
	v_fmac_f32_e32 v180, v179, v179
	v_fmac_f32_e32 v178, v177, v177
	v_add_f32_e32 v177, v180, v178
	v_fmamk_f32 v178, v148, 0xbc800000, v41
	v_fmamk_f32 v180, v148, 0xbc800000, v39
	v_add_f32_e32 v149, v149, v177
	v_fmamk_f32 v177, v148, 0xbc800000, v40
	v_fmamk_f32 v179, v148, 0xbc800000, v38
	v_mul_f32_e32 v180, v180, v180
	v_mul_f32_e32 v178, v178, v178
	v_fmac_f32_e32 v180, v179, v179
	v_fmac_f32_e32 v178, v177, v177
	v_add_f32_e32 v177, v180, v178
	v_fmamk_f32 v178, v148, 0xbc800000, v37
	v_fmamk_f32 v180, v148, 0xbc800000, v35
	v_add_f32_e32 v149, v177, v149
	v_fmamk_f32 v177, v148, 0xbc800000, v36
	v_fmamk_f32 v179, v148, 0xbc800000, v34
	v_mul_f32_e32 v180, v180, v180
	v_mul_f32_e32 v178, v178, v178
	v_fmac_f32_e32 v180, v179, v179
	v_fmac_f32_e32 v178, v177, v177
	v_add_f32_e32 v177, v180, v178
	v_add_f32_e32 v149, v177, v149
	ds_bpermute_b32 v177, v151, v149
	s_waitcnt lgkmcnt(0)
	v_add_f32_e32 v149, v149, v177
	ds_bpermute_b32 v177, v176, v149
	s_and_saveexec_b64 s[0:1], s[8:9]
	s_cbranch_execz .LBB0_39
	v_mul_f32_e32 v148, 0x3c800000, v148
	s_waitcnt lgkmcnt(0)
	v_add_f32_e32 v149, v149, v177
	ds_write_b64 v175, v[148:149] offset:4608
.LBB0_39:
	s_or_b64 exec, exec, s[0:1]
	v_add_co_u32_e32 v178, vcc, 0x140000, v146
	s_mov_b64 s[0:1], 0x140000
	s_nop 0
	v_addc_co_u32_e32 v179, vcc, 0, v147, vcc
	v_lshl_add_u64 v[148:149], v[146:147], 0, s[0:1]
	v_mov_b32_e32 v181, v33
	v_pk_mov_b32 v[178:179], v[30:31], v[32:33] op_sel:[1,0]
	v_mov_b32_e32 v180, v30
	v_pk_add_f32 v[178:179], v[178:179], v[180:181]
	s_waitcnt lgkmcnt(0)
	v_add_f32_e32 v177, v178, v179
	v_add_f32_e32 v182, 0, v177
	v_mov_b32_e32 v181, v29
	v_pk_mov_b32 v[178:179], v[26:27], v[28:29] op_sel:[1,0]
	v_mov_b32_e32 v180, v26
	v_pk_add_f32 v[178:179], v[178:179], v[180:181]
	s_nop 0
	v_pk_add_f32 v[184:185], v[178:179], v[178:179] op_sel:[0,1] op_sel_hi:[1,0]
	v_add_f32_e32 v186, v22, v23
	v_add_f32_e32 v188, v24, v25
	v_mov_b32_e32 v187, v20
	v_mov_b32_e32 v183, v18
	v_mov_b32_e32 v185, v19
	v_mov_b32_e32 v189, v21
	v_pk_add_f32 v[148:149], v[182:183], v[184:185]
	v_pk_add_f32 v[178:179], v[186:187], v[188:189]
	s_nop 0
	v_pk_add_f32 v[148:149], v[148:149], v[178:179]
	s_nop 0
	v_add_f32_e32 v148, v148, v149
	ds_bpermute_b32 v149, v151, v148
	s_waitcnt lgkmcnt(0)
	v_add_f32_e32 v148, v148, v149
	ds_bpermute_b32 v149, v176, v148
	s_waitcnt lgkmcnt(0)
	v_add_f32_e32 v148, v148, v149
	v_fmamk_f32 v177, v148, 0xbc800000, v33
	v_fmamk_f32 v179, v148, 0xbc800000, v31
	v_fmamk_f32 v149, v148, 0xbc800000, v32
	v_fmamk_f32 v178, v148, 0xbc800000, v30
	v_mul_f32_e32 v179, v179, v179
	v_mul_f32_e32 v177, v177, v177
	v_fmac_f32_e32 v179, v178, v178
	v_fmac_f32_e32 v177, v149, v149
	v_fmamk_f32 v178, v148, 0xbc800000, v29
	v_fmamk_f32 v180, v148, 0xbc800000, v27
	v_add_f32_e32 v149, v179, v177
	v_fmamk_f32 v177, v148, 0xbc800000, v28
	v_fmamk_f32 v179, v148, 0xbc800000, v26
	v_mul_f32_e32 v180, v180, v180
	v_mul_f32_e32 v178, v178, v178
	v_fmac_f32_e32 v180, v179, v179
	v_fmac_f32_e32 v178, v177, v177
	v_add_f32_e32 v177, v180, v178
	v_fmamk_f32 v178, v148, 0xbc800000, v25
	v_fmamk_f32 v180, v148, 0xbc800000, v23
	v_add_f32_e32 v149, v149, v177
	v_fmamk_f32 v177, v148, 0xbc800000, v24
	v_fmamk_f32 v179, v148, 0xbc800000, v22
	v_mul_f32_e32 v180, v180, v180
	v_mul_f32_e32 v178, v178, v178
	v_fmac_f32_e32 v180, v179, v179
	v_fmac_f32_e32 v178, v177, v177
	v_add_f32_e32 v177, v180, v178
	v_fmamk_f32 v178, v148, 0xbc800000, v21
	v_fmamk_f32 v180, v148, 0xbc800000, v19
	v_add_f32_e32 v149, v177, v149
	v_fmamk_f32 v177, v148, 0xbc800000, v20
	v_fmamk_f32 v179, v148, 0xbc800000, v18
	v_mul_f32_e32 v180, v180, v180
	v_mul_f32_e32 v178, v178, v178
	v_fmac_f32_e32 v180, v179, v179
	v_fmac_f32_e32 v178, v177, v177
	v_add_f32_e32 v177, v180, v178
	v_add_f32_e32 v149, v177, v149
	ds_bpermute_b32 v177, v151, v149
	s_waitcnt lgkmcnt(0)
	v_add_f32_e32 v149, v149, v177
	ds_bpermute_b32 v177, v176, v149
	s_and_saveexec_b64 s[0:1], s[8:9]
	s_cbranch_execz .LBB0_41
	v_mul_f32_e32 v148, 0x3c800000, v148
	s_waitcnt lgkmcnt(0)
	v_add_f32_e32 v149, v149, v177
	ds_write_b64 v175, v[148:149] offset:5120
;     __device__ __forceinline__ void operator()(f32x4 (&acc)[2][2][4][2], const Unit& u, int wr, int wc, int fr, int fq) const {
;     ...
;             for (int m = 0; m < 4; ++m) { const size_t off = (size_t)(row0 + ai * HALF + m * 16) * DM + col0; float sm = 0.f;
; #pragma unroll
;                 for (int bj = 0; bj < 2; ++bj)
; #pragma unroll
;                     for (int n = 0; n < 2; ++n) { const f32x4 x = *(const f32x4*)(xres + off + bj * HALF + n * 16); const f32x4 z = x * 1.4142135623730951f + acc[ai][bj][m][n];
;                         acc[ai][bj][m][n] = z; sm += (z[0] + z[1]) + (z[2] + z[3]); }
;                 sm += __shfl_xor(sm, 16); sm += __shfl_xor(sm, 32);
;                 const float mw = sm * (1.0f / 64.0f); float q = 0.f;
; #pragma unroll
;                 for (int bj = 0; bj < 2; ++bj)
; #pragma unroll
;                     for (int n = 0; n < 2; ++n) { const f32x4 d = acc[ai][bj][m][n] - mw; q += (d[0] * d[0] + d[1] * d[1]) + (d[2] * d[2] + d[3] * d[3]); }
;                 q += __shfl_xor(q, 16); q += __shfl_xor(q, 32);
;                 if (fq == 0) Pt[(ai * HALF + wr * 64 + m * 16 + fr) * 4 + wc] = (f32x2v){mw, q}; }
.LBB0_41:
	s_or_b64 exec, exec, s[0:1]
	s_mov_b64 s[0:1], 0x160000
	v_lshl_add_u64 v[178:179], v[146:147], 0, s[0:1]
	v_add_co_u32_e32 v146, vcc, 0x160000, v146
	s_nop 1
	v_addc_co_u32_e32 v147, vcc, 0, v147, vcc
	v_pk_fma_f32 v[148:149], v[218:219], s[72:73], v[16:17] op_sel_hi:[1,0,1]
	v_pk_fma_f32 v[146:147], v[216:217], s[72:73], v[14:15] op_sel_hi:[1,0,1]
	v_mov_b32_e32 v17, v149
	v_pk_mov_b32 v[14:15], v[146:147], v[148:149] op_sel:[1,0]
	v_mov_b32_e32 v16, v146
	v_pk_add_f32 v[14:15], v[14:15], v[16:17]
	s_nop 0
	v_add_f32_e32 v14, v14, v15
	v_add_f32_e32 v180, 0, v14
	v_pk_fma_f32 v[16:17], v[222:223], s[72:73], v[12:13] op_sel_hi:[1,0,1]
	v_pk_fma_f32 v[14:15], v[220:221], s[72:73], v[10:11] op_sel_hi:[1,0,1]
	v_mov_b32_e32 v13, v17
	v_pk_mov_b32 v[10:11], v[14:15], v[16:17] op_sel:[1,0]
	v_mov_b32_e32 v12, v14
	v_pk_add_f32 v[10:11], v[10:11], v[12:13]
	s_nop 0
	v_pk_add_f32 v[182:183], v[10:11], v[10:11] op_sel:[0,1] op_sel_hi:[1,0]
	v_pk_fma_f32 v[8:9], v[226:227], s[72:73], v[8:9] op_sel_hi:[1,0,1]
	v_pk_fma_f32 v[6:7], v[224:225], s[72:73], v[6:7] op_sel_hi:[1,0,1]
	v_add_f32_e32 v184, v6, v7
	v_add_f32_e32 v186, v8, v9
	v_pk_fma_f32 v[12:13], v[230:231], s[72:73], v[4:5] op_sel_hi:[1,0,1]
	v_pk_fma_f32 v[10:11], v[228:229], s[72:73], v[2:3] op_sel_hi:[1,0,1]
	v_mov_b32_e32 v185, v12
	v_mov_b32_e32 v181, v10
	v_mov_b32_e32 v183, v11
	v_mov_b32_e32 v187, v13
	v_pk_add_f32 v[2:3], v[180:181], v[182:183]
	v_pk_add_f32 v[4:5], v[184:185], v[186:187]
	s_nop 0
	v_pk_add_f32 v[2:3], v[2:3], v[4:5]
	s_nop 0
	v_add_f32_e32 v2, v2, v3
	ds_bpermute_b32 v3, v151, v2
	s_waitcnt lgkmcnt(0)
	v_add_f32_e32 v2, v2, v3
	ds_bpermute_b32 v3, v176, v2
	s_waitcnt lgkmcnt(0)
	v_add_f32_e32 v2, v2, v3
	v_fmamk_f32 v4, v2, 0xbc800000, v149
	v_fmamk_f32 v177, v2, 0xbc800000, v147
	v_fmamk_f32 v3, v2, 0xbc800000, v148
	v_fmamk_f32 v5, v2, 0xbc800000, v146
	v_mul_f32_e32 v177, v177, v177
	v_mul_f32_e32 v4, v4, v4
	v_fmac_f32_e32 v177, v5, v5
	v_fmac_f32_e32 v4, v3, v3
	v_fmamk_f32 v5, v2, 0xbc800000, v17
	v_fmamk_f32 v178, v2, 0xbc800000, v15
	v_add_f32_e32 v3, v177, v4
	v_fmamk_f32 v4, v2, 0xbc800000, v16
	v_fmamk_f32 v177, v2, 0xbc800000, v14
	v_mul_f32_e32 v178, v178, v178
	v_mul_f32_e32 v5, v5, v5
	v_fmac_f32_e32 v178, v177, v177
	v_fmac_f32_e32 v5, v4, v4
	v_add_f32_e32 v4, v178, v5
	v_fmamk_f32 v5, v2, 0xbc800000, v9
	v_fmamk_f32 v178, v2, 0xbc800000, v7
	v_add_f32_e32 v3, v3, v4
	v_fmamk_f32 v4, v2, 0xbc800000, v8
	v_fmamk_f32 v177, v2, 0xbc800000, v6
	v_mul_f32_e32 v178, v178, v178
	v_mul_f32_e32 v5, v5, v5
	v_fmac_f32_e32 v178, v177, v177
	v_fmac_f32_e32 v5, v4, v4
	v_add_f32_e32 v4, v178, v5
	v_fmamk_f32 v5, v2, 0xbc800000, v13
	v_fmamk_f32 v178, v2, 0xbc800000, v11
	v_add_f32_e32 v3, v4, v3
	v_fmamk_f32 v4, v2, 0xbc800000, v12
	v_fmamk_f32 v177, v2, 0xbc800000, v10
	v_mul_f32_e32 v178, v178, v178
	v_mul_f32_e32 v5, v5, v5
	v_fmac_f32_e32 v178, v177, v177
	v_fmac_f32_e32 v5, v4, v4
	v_add_f32_e32 v4, v178, v5
	v_add_f32_e32 v3, v4, v3
	ds_bpermute_b32 v4, v151, v3
	s_waitcnt lgkmcnt(0)
	v_add_f32_e32 v3, v3, v4
	ds_bpermute_b32 v4, v176, v3
	s_and_saveexec_b64 s[0:1], s[8:9]
	s_cbranch_execz .LBB0_43
	v_mul_f32_e32 v2, 0x3c800000, v2
	s_waitcnt lgkmcnt(0)
	v_add_f32_e32 v3, v3, v4
	ds_write_b64 v175, v[2:3] offset:5632

; __device__ __forceinline__ unsigned cvt_pk_bf16(float lo, float hi) { unsigned r; asm("v_cvt_pk_bf16_f32 %0, %1, %2" : "=v"(r) : "v"(lo), "v"(hi)); return r; }
; __device__ __forceinline__ float bflo(unsigned w) { return __uint_as_float(w << 16); }
; __device__ __forceinline__ float bfhi(unsigned w) { return __uint_as_float(w & 0xffff0000u); }
; __global__ void __launch_bounds__(512, 2) fwd_megakernel(Params PK) {
;     ...
;                 for (size_t id = gtid; id < (size_t)2 * 4096 * 16; id += gstride) { const int e4 = (int)(id & 15) * 4, row = (int)((id >> 4) & 4095), kv = (int)(id >> 16);
;                     const float* w2 = P.in[19 + kv] + (size_t)l * 256 * 64; const bf16_t* hr = HID + ((size_t)kv * 4096 + row) * 256; f32x4 a = (f32x4){0.f, 0.f, 0.f, 0.f};
; #pragma unroll 8
;                     for (int k = 0; k < 256; k += 2) { const unsigned hw = *(const unsigned*)(hr + k);
;                         a += *(const f32x4*)(w2 + (size_t)k * 64 + e4) * bflo(hw); a += *(const f32x4*)(w2 + (size_t)(k + 1) * 64 + e4) * bfhi(hw); }
;                     u32x2 w; w.x = cvt_pk_bf16(a[0], a[1]); w.y = cvt_pk_bf16(a[2], a[3]); *(u32x2*)(KCV + ((size_t)kv * 4096 + row) * 64 + e4) = w; } }
.LBB0_766:
	global_load_dwordx4 v[22:25], v[14:15], off offset:-28
	global_load_dwordx4 v[2:5], v[14:15], off offset:-12
	global_load_dwordx4 v[32:35], v[16:17], off offset:-3840
	global_load_dwordx4 v[36:39], v[16:17], off offset:-3584
	global_load_dwordx4 v[40:43], v[16:17], off offset:-3328
	global_load_dwordx4 v[44:47], v[16:17], off offset:-3072
	global_load_dwordx4 v[48:51], v[16:17], off offset:-2816
	global_load_dwordx4 v[52:55], v[16:17], off offset:-2560
	global_load_dwordx4 v[56:59], v[16:17], off offset:-2304
	global_load_dwordx4 v[60:63], v[16:17], off offset:-2048
	global_load_dwordx4 v[64:67], v[16:17], off offset:-1792
	global_load_dwordx4 v[68:71], v[16:17], off offset:-1536
	global_load_dwordx4 v[72:75], v[16:17], off offset:-1280
	global_load_dwordx4 v[76:79], v[16:17], off offset:-1024
	global_load_dwordx4 v[80:83], v[16:17], off offset:-768
	global_load_dwordx4 v[84:87], v[16:17], off offset:-512
	global_load_dwordx4 v[88:91], v[16:17], off offset:-256
	global_load_dwordx4 v[92:95], v[16:17], off
	s_add_i32 s13, s13, 16
	v_lshl_add_u64 v[14:15], v[14:15], 0, 32
	v_lshl_add_u64 v[16:17], v[16:17], 0, s[48:49]
	s_waitcnt vmcnt(15)
	v_lshlrev_b32_e32 v0, 16, v22
	v_pk_fma_f32 v[20:21], v[34:35], v[0:1], v[20:21] op_sel_hi:[1,0,1]
	v_pk_fma_f32 v[18:19], v[32:33], v[0:1], v[18:19] op_sel_hi:[1,0,1]
	s_waitcnt vmcnt(14)
	v_and_b32_e32 v0, 0xffff0000, v22
	v_pk_fma_f32 v[20:21], v[38:39], v[0:1], v[20:21] op_sel_hi:[1,0,1]
	v_pk_fma_f32 v[18:19], v[36:37], v[0:1], v[18:19] op_sel_hi:[1,0,1]
	s_waitcnt vmcnt(13)
	v_lshlrev_b32_e32 v0, 16, v23
	v_pk_fma_f32 v[20:21], v[42:43], v[0:1], v[20:21] op_sel_hi:[1,0,1]
	v_pk_fma_f32 v[18:19], v[40:41], v[0:1], v[18:19] op_sel_hi:[1,0,1]
	s_waitcnt vmcnt(12)
	v_and_b32_e32 v0, 0xffff0000, v23
	v_pk_fma_f32 v[20:21], v[46:47], v[0:1], v[20:21] op_sel_hi:[1,0,1]
	v_pk_fma_f32 v[18:19], v[44:45], v[0:1], v[18:19] op_sel_hi:[1,0,1]
	s_waitcnt vmcnt(11)
	v_lshlrev_b32_e32 v0, 16, v24
	v_pk_fma_f32 v[20:21], v[50:51], v[0:1], v[20:21] op_sel_hi:[1,0,1]
	v_pk_fma_f32 v[18:19], v[48:49], v[0:1], v[18:19] op_sel_hi:[1,0,1]
	s_waitcnt vmcnt(10)
	v_and_b32_e32 v0, 0xffff0000, v24
	v_pk_fma_f32 v[20:21], v[54:55], v[0:1], v[20:21] op_sel_hi:[1,0,1]
	v_pk_fma_f32 v[18:19], v[52:53], v[0:1], v[18:19] op_sel_hi:[1,0,1]
	s_waitcnt vmcnt(9)
	v_lshlrev_b32_e32 v0, 16, v25
	v_pk_fma_f32 v[20:21], v[58:59], v[0:1], v[20:21] op_sel_hi:[1,0,1]
	v_pk_fma_f32 v[18:19], v[56:57], v[0:1], v[18:19] op_sel_hi:[1,0,1]
	s_waitcnt vmcnt(8)
	v_and_b32_e32 v0, 0xffff0000, v25
	v_pk_fma_f32 v[20:21], v[62:63], v[0:1], v[20:21] op_sel_hi:[1,0,1]
	v_pk_fma_f32 v[18:19], v[60:61], v[0:1], v[18:19] op_sel_hi:[1,0,1]
	s_waitcnt vmcnt(7)
	v_lshlrev_b32_e32 v0, 16, v2
	v_pk_fma_f32 v[20:21], v[66:67], v[0:1], v[20:21] op_sel_hi:[1,0,1]
	v_pk_fma_f32 v[18:19], v[64:65], v[0:1], v[18:19] op_sel_hi:[1,0,1]
	s_waitcnt vmcnt(6)
	v_and_b32_e32 v0, 0xffff0000, v2
	v_pk_fma_f32 v[20:21], v[70:71], v[0:1], v[20:21] op_sel_hi:[1,0,1]
	v_pk_fma_f32 v[18:19], v[68:69], v[0:1], v[18:19] op_sel_hi:[1,0,1]
	s_waitcnt vmcnt(5)
	v_lshlrev_b32_e32 v0, 16, v3
	v_pk_fma_f32 v[20:21], v[74:75], v[0:1], v[20:21] op_sel_hi:[1,0,1]
	v_pk_fma_f32 v[18:19], v[72:73], v[0:1], v[18:19] op_sel_hi:[1,0,1]
	s_waitcnt vmcnt(4)
	v_and_b32_e32 v0, 0xffff0000, v3
	v_pk_fma_f32 v[20:21], v[78:79], v[0:1], v[20:21] op_sel_hi:[1,0,1]
	v_pk_fma_f32 v[18:19], v[76:77], v[0:1], v[18:19] op_sel_hi:[1,0,1]
	s_waitcnt vmcnt(3)
	v_lshlrev_b32_e32 v0, 16, v4
	v_pk_fma_f32 v[20:21], v[82:83], v[0:1], v[20:21] op_sel_hi:[1,0,1]
	v_pk_fma_f32 v[18:19], v[80:81], v[0:1], v[18:19] op_sel_hi:[1,0,1]
	s_waitcnt vmcnt(2)
	v_and_b32_e32 v0, 0xffff0000, v4
	v_pk_fma_f32 v[20:21], v[86:87], v[0:1], v[20:21] op_sel_hi:[1,0,1]
	v_pk_fma_f32 v[18:19], v[84:85], v[0:1], v[18:19] op_sel_hi:[1,0,1]
	s_waitcnt vmcnt(1)
	v_lshlrev_b32_e32 v0, 16, v5
	v_pk_fma_f32 v[20:21], v[90:91], v[0:1], v[20:21] op_sel_hi:[1,0,1]
	v_pk_fma_f32 v[18:19], v[88:89], v[0:1], v[18:19] op_sel_hi:[1,0,1]
	s_waitcnt vmcnt(0)
	v_and_b32_e32 v0, 0xffff0000, v5
	v_pk_fma_f32 v[20:21], v[94:95], v[0:1], v[20:21] op_sel_hi:[1,0,1]
	v_pk_fma_f32 v[18:19], v[92:93], v[0:1], v[18:19] op_sel_hi:[1,0,1]
	s_cmpk_gt_u32 s13, 0xfd
	s_cbranch_scc0 .LBB0_766
	v_and_b32_e32 v0, 0xfff, v12
	v_lshlrev_b64 v[4:5], 19, v[10:11]
	v_lshl_or_b32 v4, v0, 7, v4
	v_lshlrev_b32_e32 v0, 3, v8
	v_lshl_add_u64 v[8:9], v[8:9], 0, s[38:39]
	s_mov_b64 s[14:15], 0x1ffff
	v_lshl_add_u64 v[4:5], s[4:5], 0, v[4:5]
	v_and_b32_e32 v0, 0x78, v0
	v_cmp_lt_u64_e32 vcc, s[14:15], v[8:9]
	v_lshl_add_u64 v[4:5], v[4:5], 0, v[0:1]
	s_or_b64 s[8:9], vcc, s[8:9]
	v_lshl_add_u64 v[6:7], v[6:7], 0, s[90:91]
	v_cvt_pk_bf16_f32 v2, v18, v19
	v_cvt_pk_bf16_f32 v3, v20, v21
	global_store_dwordx2 v[4:5], v[2:3], off
	s_andn2_b64 exec, exec, s[8:9]
	s_cbranch_execnz .LBB0_765
